# lever 7 address arithmetic into offset immediates: attention-A LUT gather reads use one base VGPR and ds_read2_b32 offset0/offset1 immediates instead of 16 per-read address adds
# speedup vs baseline: 1.0124x; 1.0088x over previous
; #define FA_SB() __builtin_amdgcn_sched_barrier(0)
; #define FA_EXP2(J, PX, R) do { const float e0_ = __builtin_amdgcn_exp2f(PX[R]), e1_ = __builtin_amdgcn_exp2f(PX[(R) + 1]); ps += e0_; ps += e1_; PWN[(J) >> 2][(J) & 3] = cvtpk(e0_, e1_); } while (0)
; __device__ __forceinline__ void attn_unit_a(FLAS unsigned char* lds, const Unit u) {
;     ...
;         FA_BIAS(inx, pN0, pN1, cbN, ziN);
;         FA_SB();
;         if (ziN) { pN0 = __builtin_amdgcn_mfma_f32_32x32x16_bf16(kf[0], qr[0], z16, 0, 0, 0); FA_EXP2(8, pC1, 0); FA_SB(); pN1 = __builtin_amdgcn_mfma_f32_32x32x16_bf16(kf[1], qr[0], z16, 0, 0, 0); }
;         else { pN0 = __builtin_amdgcn_mfma_f32_32x32x16_bf16(kf[0], qr[0], pN0, 0, 0, 0); FA_EXP2(8, pC1, 0); FA_SB(); pN1 = __builtin_amdgcn_mfma_f32_32x32x16_bf16(kf[1], qr[0], pN1, 0, 0, 0); }
.Lgather_e:
	v_add_u32_e32 v142, s49, v210
	v_add_u32_e32 v142, 0x17600, v142
	ds_read2_b32 v[64:65], v142 offset0:0 offset1:1
	ds_read2_b32 v[80:81], v142 offset0:32 offset1:33
	ds_read2_b32 v[66:67], v142 offset0:2 offset1:3
	ds_read2_b32 v[82:83], v142 offset0:34 offset1:35
	ds_read2_b32 v[68:69], v142 offset0:8 offset1:9
	ds_read2_b32 v[84:85], v142 offset0:40 offset1:41
	ds_read2_b32 v[70:71], v142 offset0:10 offset1:11
	ds_read2_b32 v[86:87], v142 offset0:42 offset1:43
	ds_read2_b32 v[72:73], v142 offset0:16 offset1:17
	ds_read2_b32 v[88:89], v142 offset0:48 offset1:49
	ds_read2_b32 v[74:75], v142 offset0:18 offset1:19
	ds_read2_b32 v[90:91], v142 offset0:50 offset1:51
	ds_read2_b32 v[76:77], v142 offset0:24 offset1:25
	ds_read2_b32 v[92:93], v142 offset0:56 offset1:57
	ds_read2_b32 v[78:79], v142 offset0:26 offset1:27
	ds_read2_b32 v[94:95], v142 offset0:58 offset1:59
	s_waitcnt lgkmcnt(0)
	v_sub_f32_e32 v64, v64, v211
	v_sub_f32_e32 v65, v65, v211
	v_sub_f32_e32 v66, v66, v211
	v_sub_f32_e32 v67, v67, v211
	v_sub_f32_e32 v68, v68, v211
	v_sub_f32_e32 v69, v69, v211
	v_sub_f32_e32 v70, v70, v211
	v_sub_f32_e32 v71, v71, v211
	v_sub_f32_e32 v72, v72, v211
	v_sub_f32_e32 v73, v73, v211
	v_sub_f32_e32 v74, v74, v211
	v_sub_f32_e32 v75, v75, v211
	v_sub_f32_e32 v76, v76, v211
	v_sub_f32_e32 v77, v77, v211
	v_sub_f32_e32 v78, v78, v211
	v_sub_f32_e32 v79, v79, v211
	v_sub_f32_e32 v80, v80, v211
	v_sub_f32_e32 v81, v81, v211
	v_sub_f32_e32 v82, v82, v211
	v_sub_f32_e32 v83, v83, v211
	v_sub_f32_e32 v84, v84, v211
	v_sub_f32_e32 v85, v85, v211
	v_sub_f32_e32 v86, v86, v211
	v_sub_f32_e32 v87, v87, v211
	v_sub_f32_e32 v88, v88, v211
	v_sub_f32_e32 v89, v89, v211
	v_sub_f32_e32 v90, v90, v211
	v_sub_f32_e32 v91, v91, v211
	v_sub_f32_e32 v92, v92, v211
	v_sub_f32_e32 v93, v93, v211
	v_sub_f32_e32 v94, v94, v211
	v_sub_f32_e32 v95, v95, v211
	s_nop 1
	v_mfma_f32_32x32x16_bf16 v[64:79], v[204:207], v[160:163], v[64:79]
	v_exp_f32_e32 v112, v112
	v_exp_f32_e32 v113, v113
	v_add_f32_e32 v212, v110, v212
	v_add_f32_e32 v212, v111, v212
	v_mfma_f32_32x32x16_bf16 v[80:95], v[200:203], v[160:163], v[80:95]
	v_exp_f32_e32 v114, v114
	v_exp_f32_e32 v115, v115
	s_branch .Lk2_e

; #define FA_SB() __builtin_amdgcn_sched_barrier(0)
; #define FA_EXP2(J, PX, R) do { const float e0_ = __builtin_amdgcn_exp2f(PX[R]), e1_ = __builtin_amdgcn_exp2f(PX[(R) + 1]); ps += e0_; ps += e1_; PWN[(J) >> 2][(J) & 3] = cvtpk(e0_, e1_); } while (0)
; __device__ __forceinline__ void attn_unit_a(FLAS unsigned char* lds, const Unit u) {
;     ...
;         FA_BIAS(inx, pN0, pN1, cbN, ziN);
;         FA_SB();
;         if (ziN) { pN0 = __builtin_amdgcn_mfma_f32_32x32x16_bf16(kf[0], qr[0], z16, 0, 0, 0); FA_EXP2(8, pC1, 0); FA_SB(); pN1 = __builtin_amdgcn_mfma_f32_32x32x16_bf16(kf[1], qr[0], z16, 0, 0, 0); }
;         else { pN0 = __builtin_amdgcn_mfma_f32_32x32x16_bf16(kf[0], qr[0], pN0, 0, 0, 0); FA_EXP2(8, pC1, 0); FA_SB(); pN1 = __builtin_amdgcn_mfma_f32_32x32x16_bf16(kf[1], qr[0], pN1, 0, 0, 0); }
.Lgather_o:
	v_sub_u32_e32 v96, s12, v244
	v_lshl_add_u32 v206, v96, 2, v240
	v_add_u32_e32 v206, 0x1500, v206
	ds_read2_b32 v[96:97], v206 offset0:0 offset1:1
	ds_read2_b32 v[112:113], v206 offset0:32 offset1:33
	ds_read2_b32 v[98:99], v206 offset0:2 offset1:3
	ds_read2_b32 v[114:115], v206 offset0:34 offset1:35
	ds_read2_b32 v[100:101], v206 offset0:8 offset1:9
	ds_read2_b32 v[116:117], v206 offset0:40 offset1:41
	ds_read2_b32 v[102:103], v206 offset0:10 offset1:11
	ds_read2_b32 v[118:119], v206 offset0:42 offset1:43
	ds_read2_b32 v[104:105], v206 offset0:16 offset1:17
	ds_read2_b32 v[120:121], v206 offset0:48 offset1:49
	ds_read2_b32 v[106:107], v206 offset0:18 offset1:19
	ds_read2_b32 v[122:123], v206 offset0:50 offset1:51
	ds_read2_b32 v[108:109], v206 offset0:24 offset1:25
	ds_read2_b32 v[124:125], v206 offset0:56 offset1:57
	ds_read2_b32 v[110:111], v206 offset0:26 offset1:27
	ds_read2_b32 v[126:127], v206 offset0:58 offset1:59
	s_waitcnt lgkmcnt(0)
	v_sub_f32_e32 v96, v96, v211
	v_sub_f32_e32 v97, v97, v211
	v_sub_f32_e32 v98, v98, v211
	v_sub_f32_e32 v99, v99, v211
	v_sub_f32_e32 v100, v100, v211
	v_sub_f32_e32 v101, v101, v211
	v_sub_f32_e32 v102, v102, v211
	v_sub_f32_e32 v103, v103, v211
	v_sub_f32_e32 v104, v104, v211
	v_sub_f32_e32 v105, v105, v211
	v_sub_f32_e32 v106, v106, v211
	v_sub_f32_e32 v107, v107, v211
	v_sub_f32_e32 v108, v108, v211
	v_sub_f32_e32 v109, v109, v211
	v_sub_f32_e32 v110, v110, v211
	v_sub_f32_e32 v111, v111, v211
	v_sub_f32_e32 v112, v112, v211
	v_sub_f32_e32 v113, v113, v211
	v_sub_f32_e32 v114, v114, v211
	v_sub_f32_e32 v115, v115, v211
	v_sub_f32_e32 v116, v116, v211
	v_sub_f32_e32 v117, v117, v211
	v_sub_f32_e32 v118, v118, v211
	v_sub_f32_e32 v119, v119, v211
	v_sub_f32_e32 v120, v120, v211
	v_sub_f32_e32 v121, v121, v211
	v_sub_f32_e32 v122, v122, v211
	v_sub_f32_e32 v123, v123, v211
	v_sub_f32_e32 v124, v124, v211
	v_sub_f32_e32 v125, v125, v211
	v_sub_f32_e32 v126, v126, v211
	v_sub_f32_e32 v127, v127, v211
	s_nop 1
	v_mfma_f32_32x32x16_bf16 v[96:111], v[200:203], v[160:163], v[96:111]
	v_exp_f32_e32 v80, v80
	v_exp_f32_e32 v81, v81
	v_add_f32_e32 v212, v78, v212
	v_add_f32_e32 v212, v79, v212
	v_mfma_f32_32x32x16_bf16 v[112:127], v[196:199], v[160:163], v[112:127]
	v_exp_f32_e32 v82, v82
	v_exp_f32_e32 v83, v83
	s_branch .Lk2_o
